# phase_o: the four group-norm parameter loads issued with the round's other loads (counted waits) instead of late and one per store
# baseline (speedup 1.0000x reference)
; DI float bf_lo(unsigned u) { return __uint_as_float(u << 16); }
; DI float bf_hi(unsigned u) { return __uint_as_float(u & 0xffff0000u); }
; DI void phase_o(const Params& p, int l, int pi_first, int pi_end, int pi_step) {
;     ...
;   for (int pi = pi_first; pi < pi_end; pi += pi_step) {
;     const int cid = pi * 2 + (wave >> 1);
;     const bool isp = cid < NCH_P;
;     int bh, c;
;     if (isp) { bh = cid >> 7; c = cid & 127; } else { const int j = cid - NCH_P; bh = j >> 1; c = j & 1; }
;     const int b = bh >> 3, h = bh & 7;
;     const int tok = (wave & 1) * 16 + l15;
;     const size_t row = (size_t)((isp ? b * 4096 : MP + b * 64) + c * 32 + tok);
;     bf16x8 rt[2], sa[4][2]; u32x2 oi[4], ba[4], gt[4];
; #pragma unroll
;     for (int ks = 0; ks < 2; ++ks) rt[ks] = *(const bf16x8*)(p.cRT + (size_t)cid * 2048 + tok * 64 + ks * 32 + quad * 8);
; #pragma unroll
;     for (int vt = 0; vt < 4; ++vt) {
; #pragma unroll
;       for (int ks = 0; ks < 2; ++ks) sa[vt][ks] = *(const bf16x8*)(p.gS + (size_t)cid * 4096 + (vt * 16 + l15) * 64 + ks * 32 + quad * 8);
;       oi[vt] = *(const u32x2*)(p.cOI + (size_t)cid * 2048 + tok * 64 + vt * 16 + quad * 4);
;       ba[vt] = *(const u32x2*)(p.cBA + (size_t)cid * 2048 + tok * 64 + vt * 16 + quad * 4);
;       gt[vt] = *(const u32x2*)(p.z + row * NZ + C_GR + h * 64 + vt * 16 + quad * 4);
;     }
;     f32x4 ao[4];
; #pragma unroll
;     for (int vt = 0; vt < 4; ++vt) {
;       f32x4 a = (f32x4){bf_lo(oi[vt][0]), bf_hi(oi[vt][0]), bf_lo(oi[vt][1]), bf_hi(oi[vt][1])};
; #pragma unroll
;       for (int ks = 0; ks < 2; ++ks) a = __builtin_amdgcn_mfma_f32_16x16x32_bf16(sa[vt][ks], rt[ks], a, 0, 0, 0);
;       ao[vt] = a;
;     }
;     float sm = 0.f, sq = 0.f;
; #pragma unroll
;     for (int vt = 0; vt < 4; ++vt)
; #pragma unroll
;       for (int e = 0; e < 4; ++e) { sm += ao[vt][e]; sq += ao[vt][e] * ao[vt][e]; }
;     { const float a1 = __shfl_xor(sm, 16), b1 = __shfl_xor(sq, 16); sm += a1; sq += b1; }
;     { const float a1 = __shfl_xor(sm, 32), b1 = __shfl_xor(sq, 32); sm += a1; sq += b1; }
.LBB0_667:
	s_add_i32 s2, s0, 0xfffff000
	s_ashr_i32 s1, s0, 7
	s_lshr_b32 s2, s2, 1
	s_cmpk_lt_i32 s0, 0x1000
	s_cselect_b32 s24, s1, s2
	s_ashr_i32 s1, s24, 3
	s_lshl_b32 s2, s1, 12
	s_lshl_b32 s1, s1, 6
	s_addk_i32 s1, 0x4000
	s_cmpk_lt_i32 s0, 0x1000
	s_cselect_b32 s1, s2, s1
	s_and_b32 s2, s0, 0x7f
	s_cmpk_lt_i32 s0, 0x1000
	s_cselect_b32 s2, s2, s20
	s_lshl_b32 s2, s2, 5
	s_add_i32 s1, s1, s2
	v_or_b32_e32 v78, s1, v39
	s_ashr_i32 s1, s0, 31
	s_lshl_b64 s[2:3], s[0:1], 12
	v_lshl_add_u64 v[6:7], v[18:19], 0, s[2:3]
	global_load_dwordx4 v[2:5], v[6:7], off
	global_load_dwordx4 v[48:51], v[6:7], off offset:64
	s_lshl_b64 s[22:23], s[0:1], 13
	s_lshl_b32 s1, s24, 6
	v_mov_b64_e32 v[6:7], s[10:11]
	s_and_b32 s1, s1, 0x1c0
	v_lshl_add_u64 v[14:15], v[20:21], 0, s[2:3]
	v_lshl_add_u64 v[16:17], v[22:23], 0, s[2:3]
	v_mad_i64_i32 v[6:7], s[2:3], v78, s94, v[6:7]
	s_lshl_b32 s96, s1, 1
	v_lshl_add_u64 v[6:7], v[6:7], 0, s[96:97]
	v_lshl_add_u64 v[30:31], v[24:25], 0, s[22:23]
	v_lshl_add_u64 v[28:29], v[6:7], 0, v[0:1]
	global_load_dwordx4 v[6:9], v[30:31], off
	global_load_dwordx4 v[10:13], v[30:31], off offset:64
	global_load_dwordx2 v[36:37], v[14:15], off
	global_load_dwordx2 v[46:47], v[16:17], off
	global_load_dwordx2 v[44:45], v[28:29], off offset:3328
	global_load_dwordx4 v[54:57], v[30:31], off offset:2048
	global_load_dwordx4 v[58:61], v[30:31], off offset:2112
	global_load_dwordx2 v[80:81], v[14:15], off offset:32
	global_load_dwordx2 v[42:43], v[16:17], off offset:32
	global_load_dwordx2 v[40:41], v[28:29], off offset:3360
	v_add_co_u32_e32 v30, vcc, s26, v30
	s_lshl_b32 s2, s1, 2
	s_nop 0
	v_addc_co_u32_e32 v31, vcc, 0, v31, vcc
	global_load_dwordx4 v[62:65], v[30:31], off
	global_load_dwordx4 v[66:69], v[30:31], off offset:64
	global_load_dwordx2 v[82:83], v[14:15], off offset:64
	global_load_dwordx2 v[34:35], v[16:17], off offset:64
	global_load_dwordx2 v[32:33], v[28:29], off offset:3392
	global_load_dwordx4 v[70:73], v[30:31], off offset:2048
	global_load_dwordx4 v[74:77], v[30:31], off offset:2112
	global_load_dwordx2 v[84:85], v[14:15], off offset:96
	s_nop 0
	global_load_dwordx2 v[30:31], v[16:17], off offset:96
	s_nop 0
	global_load_dwordx2 v[28:29], v[28:29], off offset:3424
	s_mov_b32 s3, s97
	v_lshl_add_u64 v[226:227], v[26:27], 0, s[2:3]
	global_load_dwordx4 v[112:115], v[226:227], off
	global_load_dwordx4 v[116:119], v[226:227], off offset:64
	global_load_dwordx4 v[120:123], v[226:227], off offset:128
	global_load_dwordx4 v[222:225], v[226:227], off offset:192
	v_ashrrev_i32_e32 v79, 31, v78
	s_add_i32 s21, s21, s42
	s_add_i32 s0, s0, s25
	s_cmpk_lt_i32 s21, 0x800
	s_waitcnt vmcnt(21)
	v_lshlrev_b32_e32 v14, 16, v36
	v_and_b32_e32 v15, 0xffff0000, v36
	v_lshlrev_b32_e32 v16, 16, v37
	v_and_b32_e32 v17, 0xffff0000, v37
	s_nop 1
	v_mfma_f32_16x16x32_bf16 v[6:9], v[6:9], v[2:5], v[14:17]
	v_mfma_f32_16x16x32_bf16 v[14:17], v[10:13], v[48:51], v[6:9]
	s_waitcnt vmcnt(16)
	s_nop 5
	v_lshlrev_b32_e32 v6, 16, v80
	v_and_b32_e32 v7, 0xffff0000, v80
	v_lshlrev_b32_e32 v8, 16, v81
	v_and_b32_e32 v9, 0xffff0000, v81
	v_add_f32_e32 v36, 0, v14
	v_add_f32_e32 v36, v15, v36
	v_mfma_f32_16x16x32_bf16 v[6:9], v[54:57], v[2:5], v[6:9]
	s_waitcnt vmcnt(6)
	v_lshlrev_b32_e32 v54, 16, v84
	v_and_b32_e32 v55, 0xffff0000, v84
	v_lshlrev_b32_e32 v56, 16, v85
	v_mfma_f32_16x16x32_bf16 v[10:13], v[58:61], v[48:51], v[6:9]
	v_and_b32_e32 v57, 0xffff0000, v85
	v_add_f32_e32 v36, v16, v36
	v_mul_f32_e32 v38, v15, v15
	v_lshlrev_b32_e32 v6, 16, v82
	v_and_b32_e32 v7, 0xffff0000, v82
	v_lshlrev_b32_e32 v8, 16, v83
	v_and_b32_e32 v9, 0xffff0000, v83
	v_add_f32_e32 v36, v17, v36
	v_fmac_f32_e32 v38, v14, v14
	v_mfma_f32_16x16x32_bf16 v[6:9], v[62:65], v[2:5], v[6:9]
	v_mov_b32_e32 v37, v17
	v_fmac_f32_e32 v38, v16, v16
	v_lshlrev_b32_e32 v58, 16, v46
	v_mfma_f32_16x16x32_bf16 v[2:5], v[70:73], v[2:5], v[54:57]
	v_and_b32_e32 v59, 0xffff0000, v46
	v_lshlrev_b32_e32 v46, 16, v47
	v_and_b32_e32 v47, 0xffff0000, v47
	v_mfma_f32_16x16x32_bf16 v[6:9], v[66:69], v[48:51], v[6:9]
	v_mfma_f32_16x16x32_bf16 v[2:5], v[74:77], v[48:51], v[2:5]
	v_add_f32_e32 v48, v10, v36
	v_mov_b32_e32 v36, v10
	v_pk_mul_f32 v[36:37], v[36:37], v[36:37]
	s_nop 0
	v_add_f32_e32 v37, v37, v38
	v_add_f32_e32 v38, v36, v37
	v_add_f32_e32 v36, v11, v48
	v_add_f32_e32 v50, v12, v36
	v_pk_mul_f32 v[36:37], v[12:13], v[12:13]
	v_pk_mul_f32 v[48:49], v[10:11], v[10:11]
	s_nop 0
	v_add_f32_e32 v37, v49, v38
	v_add_f32_e32 v38, v36, v37
	v_add_f32_e32 v36, v13, v50
	v_add_f32_e32 v48, v6, v36
	v_mov_b32_e32 v36, v6
	v_mov_b32_e32 v37, v13
	v_pk_mul_f32 v[36:37], v[36:37], v[36:37]
	s_nop 0
	v_add_f32_e32 v37, v37, v38
	v_add_f32_e32 v38, v36, v37
	v_add_f32_e32 v36, v7, v48
	v_add_f32_e32 v50, v8, v36
	v_pk_mul_f32 v[36:37], v[8:9], v[8:9]
	v_pk_mul_f32 v[48:49], v[6:7], v[6:7]
	s_nop 0
	v_add_f32_e32 v37, v49, v38
	v_add_f32_e32 v38, v36, v37
	v_add_f32_e32 v36, v9, v50
	v_add_f32_e32 v48, v2, v36
	v_mov_b32_e32 v36, v2
	v_mov_b32_e32 v37, v9
	v_pk_mul_f32 v[36:37], v[36:37], v[36:37]
	v_pk_mul_f32 v[50:51], v[2:3], v[2:3]
	v_add_f32_e32 v37, v37, v38
	v_add_f32_e32 v36, v36, v37
	v_add_f32_e32 v36, v51, v36
	v_lshl_add_u64 v[50:51], v[26:27], 0, s[2:3]
	v_add_f32_e32 v37, v3, v48
	v_pk_mul_f32 v[48:49], v[4:5], v[4:5]
	v_add_f32_e32 v37, v4, v37
	v_add_f32_e32 v48, v48, v36
	v_mul_f32_e32 v36, v5, v5
	v_mov_b32_e32 v49, v5
	v_pk_add_f32 v[36:37], v[48:49], v[36:37]
	ds_bpermute_b32 v49, v52, v37
	ds_bpermute_b32 v48, v52, v36
	s_waitcnt lgkmcnt(0)
; DI unsigned pk2(float a, float b) { f32x2 v = {a, b}; bfv2 r = __builtin_convertvector(v, bfv2); return __builtin_bit_cast(unsigned, r); }
; DI float bf_lo(unsigned u) { return __uint_as_float(u << 16); }
; DI float bf_hi(unsigned u) { return __uint_as_float(u & 0xffff0000u); }
; DI void phase_o(const Params& p, int l, int pi_first, int pi_end, int pi_step) {
;     ...
;     const float mean = sm * (1.0f / 64.0f);
;     const float rstd = rsqrtf(fmaxf(sq * (1.0f / 64.0f) - mean * mean, 0.f) + 64e-5f);
;     const float* lg = p.lnx_g + l * 512 + h * 64;
; #pragma unroll
;     for (int vt = 0; vt < 4; ++vt) {
;       const int vv = vt * 16 + quad * 4;
;       const f32x4 g4 = *(const f32x4*)(lg + vv);
;       const float y0 = ((ao[vt][0] - mean) * rstd * g4[0] + bf_lo(ba[vt][0])) * bf_lo(gt[vt][0]);
;       const float y1 = ((ao[vt][1] - mean) * rstd * g4[1] + bf_hi(ba[vt][0])) * bf_hi(gt[vt][0]);
;       const float y2 = ((ao[vt][2] - mean) * rstd * g4[2] + bf_lo(ba[vt][1])) * bf_lo(gt[vt][1]);
;       const float y3 = ((ao[vt][3] - mean) * rstd * g4[3] + bf_hi(ba[vt][1])) * bf_hi(gt[vt][1]);
;       u32x2 ov; ov[0] = pk2(y0, y1); ov[1] = pk2(y2, y3);
;       *(u32x2*)(p.o_r + row * 512 + h * 64 + vv) = ov;
;     }
	v_pk_add_f32 v[36:37], v[36:37], v[48:49]
	ds_bpermute_b32 v49, v53, v37
	ds_bpermute_b32 v48, v53, v36
	s_waitcnt lgkmcnt(0)
	v_pk_add_f32 v[36:37], v[36:37], v[48:49]
	s_nop 0
	v_pk_mul_f32 v[36:37], v[36:37], s[44:45] op_sel_hi:[1,0]
	s_nop 0
	v_fma_f32 v38, -v37, v37, v36
	v_max_f32_e32 v38, 0, v38
	v_add_f32_e32 v38, 0x3a27c5ac, v38
	v_cmp_gt_f32_e32 vcc, s34, v38
	v_mul_f32_e32 v48, 0x4b800000, v38
	v_pk_add_f32 v[14:15], v[14:15], v[36:37] op_sel:[0,1] neg_lo:[0,1] neg_hi:[0,1]
	v_cndmask_b32_e32 v38, v38, v48, vcc
	v_rsq_f32_e32 v38, v38
	v_pk_add_f32 v[16:17], v[16:17], v[36:37] op_sel:[0,1] neg_lo:[0,1] neg_hi:[0,1]
	v_pk_add_f32 v[10:11], v[10:11], v[36:37] op_sel:[0,1] neg_lo:[0,1] neg_hi:[0,1]
	v_pk_add_f32 v[12:13], v[12:13], v[36:37] op_sel:[0,1] neg_lo:[0,1] neg_hi:[0,1]
	v_mul_f32_e32 v48, 0x45800000, v38
	v_cndmask_b32_e32 v38, v38, v48, vcc
	v_pk_mul_f32 v[14:15], v[14:15], v[38:39] op_sel_hi:[1,0]
	v_pk_mul_f32 v[16:17], v[16:17], v[38:39] op_sel_hi:[1,0]
	v_lshlrev_b64 v[48:49], 10, v[78:79]
	v_pk_mul_f32 v[10:11], v[10:11], v[38:39] op_sel_hi:[1,0]
	v_pk_mul_f32 v[12:13], v[12:13], v[38:39] op_sel_hi:[1,0]
	v_pk_add_f32 v[6:7], v[6:7], v[36:37] op_sel:[0,1] neg_lo:[0,1] neg_hi:[0,1]
	v_pk_add_f32 v[8:9], v[8:9], v[36:37] op_sel:[0,1] neg_lo:[0,1] neg_hi:[0,1]
	v_pk_mul_f32 v[6:7], v[6:7], v[38:39] op_sel_hi:[1,0]
	v_pk_mul_f32 v[8:9], v[8:9], v[38:39] op_sel_hi:[1,0]
	v_pk_add_f32 v[2:3], v[2:3], v[36:37] op_sel:[0,1] neg_lo:[0,1] neg_hi:[0,1]
	v_pk_add_f32 v[4:5], v[4:5], v[36:37] op_sel:[0,1] neg_lo:[0,1] neg_hi:[0,1]
	v_pk_mul_f32 v[2:3], v[2:3], v[38:39] op_sel_hi:[1,0]
	v_pk_mul_f32 v[4:5], v[4:5], v[38:39] op_sel_hi:[1,0]
	s_waitcnt vmcnt(3)
	v_mov_b32_e32 v54, v112
	v_mov_b32_e32 v55, v113
	v_mov_b32_e32 v56, v114
	v_mov_b32_e32 v57, v115
	v_pk_fma_f32 v[14:15], v[54:55], v[14:15], v[58:59]
	v_lshlrev_b32_e32 v54, 16, v44
	v_and_b32_e32 v55, 0xffff0000, v44
	v_pk_mul_f32 v[14:15], v[14:15], v[54:55]
	v_pk_fma_f32 v[16:17], v[56:57], v[16:17], v[46:47]
	v_lshlrev_b32_e32 v44, 16, v45
	v_and_b32_e32 v45, 0xffff0000, v45
	v_pk_mul_f32 v[44:45], v[16:17], v[44:45]
	v_cvt_pk_bf16_f32 v16, v14, v15
	v_lshl_add_u64 v[14:15], s[52:53], 0, v[48:49]
	v_lshl_add_u64 v[14:15], v[14:15], 0, s[96:97]
	v_cvt_pk_bf16_f32 v17, v44, v45
	v_lshl_add_u64 v[14:15], v[14:15], 0, v[0:1]
	global_store_dwordx2 v[14:15], v[16:17], off
	v_lshlrev_b32_e32 v16, 16, v42
	v_and_b32_e32 v17, 0xffff0000, v42
	s_waitcnt vmcnt(3)
	v_mov_b32_e32 v44, v116
	v_mov_b32_e32 v45, v117
	v_mov_b32_e32 v46, v118
	v_mov_b32_e32 v47, v119
	v_pk_fma_f32 v[10:11], v[44:45], v[10:11], v[16:17]
	v_lshlrev_b32_e32 v16, 16, v40
	v_and_b32_e32 v17, 0xffff0000, v40
	v_pk_mul_f32 v[10:11], v[10:11], v[16:17]
	v_lshlrev_b32_e32 v16, 16, v43
	v_and_b32_e32 v17, 0xffff0000, v43
	v_pk_fma_f32 v[12:13], v[46:47], v[12:13], v[16:17]
	v_lshlrev_b32_e32 v16, 16, v41
	v_and_b32_e32 v17, 0xffff0000, v41
	v_pk_mul_f32 v[12:13], v[12:13], v[16:17]
	v_cvt_pk_bf16_f32 v10, v10, v11
	v_cvt_pk_bf16_f32 v11, v12, v13
	global_store_dwordx2 v[14:15], v[10:11], off offset:32
	v_lshlrev_b32_e32 v16, 16, v34
	v_and_b32_e32 v17, 0xffff0000, v34
	s_waitcnt vmcnt(3)
	v_mov_b32_e32 v10, v120
	v_mov_b32_e32 v11, v121
	v_mov_b32_e32 v12, v122
	v_mov_b32_e32 v13, v123
	v_pk_fma_f32 v[6:7], v[10:11], v[6:7], v[16:17]
	v_lshlrev_b32_e32 v10, 16, v32
	v_and_b32_e32 v11, 0xffff0000, v32
	v_pk_mul_f32 v[6:7], v[6:7], v[10:11]
	v_lshlrev_b32_e32 v10, 16, v35
	v_and_b32_e32 v11, 0xffff0000, v35
	v_pk_fma_f32 v[8:9], v[12:13], v[8:9], v[10:11]
	v_lshlrev_b32_e32 v10, 16, v33
	v_and_b32_e32 v11, 0xffff0000, v33
	v_pk_mul_f32 v[8:9], v[8:9], v[10:11]
	v_cvt_pk_bf16_f32 v6, v6, v7
	v_cvt_pk_bf16_f32 v7, v8, v9
	global_store_dwordx2 v[14:15], v[6:7], off offset:64
	v_lshlrev_b32_e32 v10, 16, v30
	v_and_b32_e32 v11, 0xffff0000, v30
	s_waitcnt vmcnt(3)
	v_mov_b32_e32 v6, v222
	v_mov_b32_e32 v7, v223
	v_mov_b32_e32 v8, v224
	v_mov_b32_e32 v9, v225
	v_pk_fma_f32 v[2:3], v[6:7], v[2:3], v[10:11]
	v_lshlrev_b32_e32 v6, 16, v28
	v_and_b32_e32 v7, 0xffff0000, v28
	v_pk_mul_f32 v[2:3], v[2:3], v[6:7]
	v_lshlrev_b32_e32 v6, 16, v31
	v_and_b32_e32 v7, 0xffff0000, v31
	v_pk_fma_f32 v[4:5], v[8:9], v[4:5], v[6:7]
	v_lshlrev_b32_e32 v6, 16, v29
	v_and_b32_e32 v7, 0xffff0000, v29
	v_pk_mul_f32 v[4:5], v[4:5], v[6:7]
	v_cvt_pk_bf16_f32 v2, v2, v3
	v_cvt_pk_bf16_f32 v3, v4, v5
	global_store_dwordx2 v[14:15], v[2:3], off offset:96
	s_cbranch_scc1 .LBB0_667
